# stack + L0 attention bias-table fill: 8 loads in flight per unit instead of serial rounds
# speedup vs baseline: 1.0459x; 1.0127x over previous
.LBB0_870:
	v_exp_f32_e32 v34, v34
	v_exp_f32_e32 v50, v50
	v_exp_f32_e32 v35, v35
	v_exp_f32_e32 v51, v51
	v_exp_f32_e32 v36, v36
	v_add_f32_e32 v66, v50, v34
	v_add_f32_e32 v66, 0, v66
	v_add_f32_e32 v67, v51, v35
	v_add_f32_e32 v66, v67, v66
	v_exp_f32_e32 v67, v52
	v_exp_f32_e32 v37, v37
	v_exp_f32_e32 v38, v38
	v_exp_f32_e32 v54, v54
	v_add_f32_e32 v52, v67, v36
	v_add_f32_e32 v52, v52, v66
	v_exp_f32_e32 v66, v53
	v_exp_f32_e32 v39, v39
	v_exp_f32_e32 v55, v55
	v_exp_f32_e32 v40, v40
	v_exp_f32_e32 v56, v56
	v_add_f32_e32 v53, v66, v37
	v_exp_f32_e32 v41, v41
	v_exp_f32_e32 v57, v57
	v_add_f32_e32 v52, v53, v52
	v_add_f32_e32 v53, v54, v38
	v_add_f32_e32 v52, v53, v52
	v_add_f32_e32 v53, v55, v39
	v_add_f32_e32 v52, v53, v52
	v_add_f32_e32 v53, v56, v40
	v_add_f32_e32 v52, v53, v52
	v_add_f32_e32 v53, v57, v41
	v_cvt_pk_bf16_f32 v34, v34, v35
	v_cvt_pk_bf16_f32 v35, v36, v37
	v_cvt_pk_bf16_f32 v36, v38, v39
	v_cvt_pk_bf16_f32 v37, v40, v41
	ds_read_b64_tr_b16 v[38:39], v115
	ds_read_b64_tr_b16 v[40:41], v115 offset:1152
	s_waitcnt lgkmcnt(0)
	v_mfma_f32_32x32x16_bf16 v[18:33], v[38:41], v[34:37], v[18:33]
	ds_read_b64_tr_b16 v[38:39], v115 offset:64
	ds_read_b64_tr_b16 v[40:41], v115 offset:1216
	v_exp_f32_e32 v42, v42
	v_exp_f32_e32 v43, v43
	v_exp_f32_e32 v44, v44
	v_exp_f32_e32 v45, v45
	v_exp_f32_e32 v46, v46
	v_exp_f32_e32 v47, v47
	v_exp_f32_e32 v48, v48
	v_exp_f32_e32 v49, v49
	s_waitcnt lgkmcnt(0)
	v_mfma_f32_32x32x16_bf16 v[2:17], v[38:41], v[34:37], v[2:17]
	v_cvt_pk_bf16_f32 v34, v42, v43
	v_cvt_pk_bf16_f32 v35, v44, v45
	v_cvt_pk_bf16_f32 v36, v46, v47
	v_cvt_pk_bf16_f32 v37, v48, v49
	ds_read_b64_tr_b16 v[38:39], v115 offset:2304
	ds_read_b64_tr_b16 v[40:41], v115 offset:3456
	v_exp_f32_e32 v58, v58
	v_exp_f32_e32 v59, v59
	s_waitcnt lgkmcnt(0)
	v_mfma_f32_32x32x16_bf16 v[18:33], v[38:41], v[34:37], v[18:33]
	ds_read_b64_tr_b16 v[38:39], v115 offset:2368
	ds_read_b64_tr_b16 v[40:41], v115 offset:3520
	v_exp_f32_e32 v60, v60
	v_exp_f32_e32 v61, v61
	v_exp_f32_e32 v62, v62
	v_exp_f32_e32 v63, v63
	v_exp_f32_e32 v64, v64
	v_exp_f32_e32 v65, v65
	s_waitcnt lgkmcnt(0)
	v_mfma_f32_32x32x16_bf16 v[2:17], v[38:41], v[34:37], v[2:17]
	v_cvt_pk_bf16_f32 v34, v50, v51
	v_cvt_pk_bf16_f32 v35, v67, v66
	v_cvt_pk_bf16_f32 v36, v54, v55
	v_cvt_pk_bf16_f32 v37, v56, v57
	ds_read_b64_tr_b16 v[38:39], v115 offset:4608
	ds_read_b64_tr_b16 v[40:41], v115 offset:5760
	v_add_f32_e32 v52, v53, v52
	v_add_f32_e32 v53, v58, v42
	s_waitcnt lgkmcnt(0)
	v_mfma_f32_32x32x16_bf16 v[18:33], v[38:41], v[34:37], v[18:33]
	ds_read_b64_tr_b16 v[38:39], v115 offset:4672
	ds_read_b64_tr_b16 v[40:41], v115 offset:5824
	v_add_f32_e32 v52, v53, v52
	v_add_f32_e32 v53, v59, v43
	v_add_f32_e32 v52, v53, v52
	v_add_f32_e32 v53, v60, v44
	v_add_f32_e32 v52, v53, v52
	v_add_f32_e32 v53, v61, v45
	s_waitcnt lgkmcnt(0)
	v_mfma_f32_32x32x16_bf16 v[2:17], v[38:41], v[34:37], v[2:17]
	v_cvt_pk_bf16_f32 v34, v58, v59
	v_cvt_pk_bf16_f32 v35, v60, v61
	v_cvt_pk_bf16_f32 v36, v62, v63
	v_cvt_pk_bf16_f32 v37, v64, v65
	ds_read_b64_tr_b16 v[38:39], v115 offset:6912
	ds_read_b64_tr_b16 v[40:41], v115 offset:8064
	v_add_f32_e32 v52, v53, v52
	v_add_f32_e32 v53, v62, v46
	s_waitcnt lgkmcnt(0)
	v_mfma_f32_32x32x16_bf16 v[18:33], v[38:41], v[34:37], v[18:33]
	ds_read_b64_tr_b16 v[38:39], v115 offset:6976
	ds_read_b64_tr_b16 v[40:41], v115 offset:8128
	v_add_f32_e32 v52, v53, v52
	v_add_f32_e32 v53, v63, v47
	v_add_f32_e32 v52, v53, v52
	v_add_f32_e32 v53, v64, v48
	v_add_f32_e32 v52, v53, v52
	v_add_f32_e32 v53, v65, v49
	s_waitcnt lgkmcnt(0)
	v_mfma_f32_32x32x16_bf16 v[2:17], v[38:41], v[34:37], v[2:17]
	v_add_f32_e32 v52, v53, v52
	v_mov_b32_e32 v53, v52
	s_movk_i32 s2, 0x1d1
	s_nop 0
	v_permlane32_swap_b32_e32 v52, v53
	v_cmp_gt_i32_e32 vcc, s2, v114
	s_barrier
	s_and_saveexec_b64 s[8:9], vcc
	s_cbranch_execz .LBB0_880
	s_ashr_i32 s2, s68, 6
	s_mul_i32 s10, s2, 0x1d1
	s_ashr_i32 s11, s10, 31
	s_lshl_b64 s[10:11], s[10:11], 2
	s_add_u32 s10, s86, s10
	s_addc_u32 s11, s87, s11
	v_lshlrev_b32_e32 v34, 2, v114
	v_readlane_b32 s2, v254, 39
	v_cmp_gt_u32_e32 vcc, 17, v114
	global_load_dword v36, v34, s[10:11]
	global_load_dword v37, v34, s[10:11] offset:256
	global_load_dword v38, v34, s[10:11] offset:512
	global_load_dword v39, v34, s[10:11] offset:768
	global_load_dword v40, v34, s[10:11] offset:1024
	global_load_dword v41, v34, s[10:11] offset:1280
	global_load_dword v42, v34, s[10:11] offset:1536
	s_and_saveexec_b64 s[12:13], vcc
	global_load_dword v43, v34, s[10:11] offset:1792
	s_mov_b64 exec, s[12:13]
	v_add_u32_e32 v35, s2, v34
	s_waitcnt vmcnt(0)
	v_mul_f32_e32 v36, 0x3fb8aa3b, v36
	v_mul_f32_e32 v37, 0x3fb8aa3b, v37
	v_mul_f32_e32 v38, 0x3fb8aa3b, v38
	v_mul_f32_e32 v39, 0x3fb8aa3b, v39
	v_mul_f32_e32 v40, 0x3fb8aa3b, v40
	v_mul_f32_e32 v41, 0x3fb8aa3b, v41
	v_mul_f32_e32 v42, 0x3fb8aa3b, v42
	v_mul_f32_e32 v43, 0x3fb8aa3b, v43
	ds_write_b32 v35, v36
	ds_write_b32 v35, v37 offset:256
	ds_write_b32 v35, v38 offset:512
	ds_write_b32 v35, v39 offset:768
	ds_write_b32 v35, v40 offset:1024
	ds_write_b32 v35, v41 offset:1280
	ds_write_b32 v35, v42 offset:1536
	s_and_saveexec_b64 s[12:13], vcc
	ds_write_b32 v35, v43 offset:1792
	s_mov_b64 exec, s[12:13]
